# EpiBranch epilogue: 16 serialized gate loads issued as two batches of 8 into free fragment VGPRs, counted vmcnt waits
# speedup vs baseline: 1.0158x; 1.0158x over previous
; __device__ __forceinline__ float sigm(float x) { return __builtin_amdgcn_rcpf(1.f + __expf(-x)); }
;     __device__ __forceinline__ void operator()(const f32x4 (&acc)[2][2][4][2], const Unit& u, int wr, int wc, int fr, int fq) const {
;     ...
;             for (int m = 0; m < 4; ++m) { const int row = row0 + ai * HALF + m * 16;
; #pragma unroll
;                 for (int bj = 0; bj < 2; ++bj) { const int col = col0 + bj * HALF;
;                     float gt[8]; unpack8(*(const u32x4*)(H + (size_t)row * NPAD + C_GATE + g * D + col), gt);
;                     float v[8];
; #pragma unroll
;                     for (int e = 0; e < 4; ++e) { v[e] = sigm(gt[e]) * acc[ai][bj][m][0][e]; v[4 + e] = sigm(gt[4 + e]) * acc[ai][bj][m][1][e]; }
;                     if (u.split) { float* cp = SCTX + ((size_t)u.slot * 512 + (row - u.pm * BM + (u.pm ? 256 : 0))) * D + col;
;                         *(f32x4*)cp = (f32x4){v[0], v[1], v[2], v[3]}; *(f32x4*)(cp + 4) = (f32x4){v[4], v[5], v[6], v[7]}; }
.LBB0_883:
	s_lshl_b32 s11, s48, 8
	v_add_u32_e32 v142, s11, v148
	s_lshl_b32 s20, s4, 11
	v_mov_b64_e32 v[144:145], s[60:61]
	v_lshl_or_b32 v140, s6, 8, v150
	s_ashr_i32 s21, s20, 31
	v_mad_i64_i32 v[144:145], s[6:7], v142, s43, v[144:145]
	v_lshl_add_u64 v[144:145], s[20:21], 1, v[144:145]
	v_ashrrev_i32_e32 v141, 31, v140
	v_lshl_add_u64 v[146:147], v[140:141], 1, v[144:145]
	v_mov_b64_e32 v[214:215], v[146:147]
	s_mov_b64 s[6:7], 0x5840
	v_lshl_add_u64 v[216:217], v[146:147], 0, s[6:7]
	global_load_dwordx4 v[164:167], v[216:217], off
	global_load_dwordx4 v[168:171], v[216:217], off offset:256
	s_mov_b64 s[6:7], 0x8f840
	v_lshl_add_u64 v[216:217], v[146:147], 0, s[6:7]
	global_load_dwordx4 v[172:175], v[216:217], off
	global_load_dwordx4 v[176:179], v[216:217], off offset:256
	s_mov_b64 s[6:7], 0x119840
	v_lshl_add_u64 v[216:217], v[146:147], 0, s[6:7]
	global_load_dwordx4 v[180:183], v[216:217], off
	global_load_dwordx4 v[184:187], v[216:217], off offset:256
	s_mov_b64 s[6:7], 0x1a3840
	v_lshl_add_u64 v[216:217], v[146:147], 0, s[6:7]
	global_load_dwordx4 v[188:191], v[216:217], off
	global_load_dwordx4 v[192:195], v[216:217], off offset:256
	v_add_co_u32_e32 v144, vcc, s66, v146
	s_cmp_gt_i32 s4, 0
	s_nop 0
	v_addc_co_u32_e32 v145, vcc, 0, v147, vcc
	s_cselect_b64 s[4:5], -1, 0
	s_cmp_lg_u32 s9, 0
	s_cselect_b64 s[22:23], -1, 0
	s_cmp_eq_u32 s9, 0
	s_waitcnt vmcnt(7)
	v_mov_b64_e32 v[152:153], v[164:165]
	v_mov_b64_e32 v[154:155], v[166:167]
	v_lshlrev_b32_e32 v143, 16, v152
	v_and_b32_e32 v144, 0xffff0000, v152
	v_lshlrev_b32_e32 v145, 16, v153
	v_and_b32_e32 v152, 0xffff0000, v153
	v_lshlrev_b32_e32 v153, 16, v154
	v_and_b32_e32 v154, 0xffff0000, v154
	v_lshlrev_b32_e32 v156, 16, v155
	v_and_b32_e32 v155, 0xffff0000, v155
	v_mul_f32_e32 v143, 0xbfb8aa3b, v143
	v_mul_f32_e32 v153, 0xbfb8aa3b, v153
	v_mul_f32_e32 v144, 0xbfb8aa3b, v144
	v_mul_f32_e32 v154, 0xbfb8aa3b, v154
	v_mul_f32_e32 v145, 0xbfb8aa3b, v145
	v_mul_f32_e32 v156, 0xbfb8aa3b, v156
	v_mul_f32_e32 v152, 0xbfb8aa3b, v152
	v_mul_f32_e32 v155, 0xbfb8aa3b, v155
	v_exp_f32_e32 v143, v143
	v_exp_f32_e32 v153, v153
	v_exp_f32_e32 v144, v144
	v_exp_f32_e32 v154, v154
	v_exp_f32_e32 v145, v145
	v_exp_f32_e32 v156, v156
	v_exp_f32_e32 v152, v152
	v_exp_f32_e32 v155, v155
	v_add_f32_e32 v143, 1.0, v143
	v_add_f32_e32 v153, 1.0, v153
	v_add_f32_e32 v157, 1.0, v144
	v_add_f32_e32 v154, 1.0, v154
	v_add_f32_e32 v158, 1.0, v145
	v_add_f32_e32 v156, 1.0, v156
	v_add_f32_e32 v159, 1.0, v152
	v_add_f32_e32 v160, 1.0, v155
	v_rcp_f32_e32 v144, v143
	v_rcp_f32_e32 v152, v153
	v_rcp_f32_e32 v145, v157
	v_rcp_f32_e32 v153, v154
	v_rcp_f32_e32 v154, v158
	v_rcp_f32_e32 v156, v156
	v_rcp_f32_e32 v155, v159
	v_rcp_f32_e32 v157, v160
	v_pk_mul_f32 v[128:129], v[128:129], v[144:145]
	v_pk_mul_f32 v[124:125], v[124:125], v[152:153]
	v_pk_mul_f32 v[130:131], v[130:131], v[154:155]
	v_pk_mul_f32 v[126:127], v[126:127], v[156:157]
	s_cbranch_scc1 .LBB0_885
	s_ashr_i32 s9, s8, 31
	s_cmp_eq_u32 s48, 0
	s_cselect_b32 s6, 0, 0x100
	v_add_u32_e32 v144, s6, v148
	s_lshl_b64 s[6:7], s[8:9], 22
	v_ashrrev_i32_e32 v145, 31, v144
	s_add_u32 s6, s28, s6
	s_addc_u32 s7, s29, s7
	v_lshlrev_b64 v[144:145], 13, v[144:145]
	v_lshl_add_u64 v[144:145], s[6:7], 0, v[144:145]
	v_lshl_add_u64 v[144:145], v[140:141], 2, v[144:145]
	s_mov_b64 s[6:7], 0
	global_store_dwordx4 v[144:145], v[128:131], off
	global_store_dwordx4 v[144:145], v[124:127], off offset:16
	s_branch .LBB0_886

; __device__ __forceinline__ float sigm(float x) { return __builtin_amdgcn_rcpf(1.f + __expf(-x)); }
;     __device__ __forceinline__ void operator()(const f32x4 (&acc)[2][2][4][2], const Unit& u, int wr, int wc, int fr, int fq) const {
;     ...
;             for (int m = 0; m < 4; ++m) { const int row = row0 + ai * HALF + m * 16;
; #pragma unroll
;                 for (int bj = 0; bj < 2; ++bj) { const int col = col0 + bj * HALF;
;                     float gt[8]; unpack8(*(const u32x4*)(H + (size_t)row * NPAD + C_GATE + g * D + col), gt);
;                     float v[8];
; #pragma unroll
;                     for (int e = 0; e < 4; ++e) { v[e] = sigm(gt[e]) * acc[ai][bj][m][0][e]; v[4 + e] = sigm(gt[4 + e]) * acc[ai][bj][m][1][e]; }
;                     if (u.split) { float* cp = SCTX + ((size_t)u.slot * 512 + (row - u.pm * BM + (u.pm ? 256 : 0))) * D + col;
;                         *(f32x4*)cp = (f32x4){v[0], v[1], v[2], v[3]}; *(f32x4*)(cp + 4) = (f32x4){v[4], v[5], v[6], v[7]}; }
.LBB0_890:
	s_mov_b64 s[6:7], 0x5840
	v_lshl_add_u64 v[124:125], v[146:147], 0, s[6:7]
	s_andn2_b64 vcc, exec, s[22:23]
	s_waitcnt vmcnt(6)
	v_mov_b64_e32 v[124:125], v[168:169]
	v_mov_b64_e32 v[126:127], v[170:171]
	v_lshlrev_b32_e32 v130, 16, v125
	v_and_b32_e32 v131, 0xffff0000, v125
	v_lshlrev_b32_e32 v125, 16, v126
	v_mul_f32_e32 v125, 0xbfb8aa3b, v125
	v_exp_f32_e32 v125, v125
	v_lshlrev_b32_e32 v128, 16, v124
	v_and_b32_e32 v129, 0xffff0000, v124
	v_and_b32_e32 v143, 0xffff0000, v126
	v_add_f32_e32 v125, 1.0, v125
	v_mul_f32_e32 v124, 0xbfb8aa3b, v128
	v_rcp_f32_e32 v126, v125
	v_mul_f32_e32 v125, 0xbfb8aa3b, v129
	v_exp_f32_e32 v124, v124
	v_exp_f32_e32 v125, v125
	v_lshlrev_b32_e32 v146, 16, v127
	v_and_b32_e32 v147, 0xffff0000, v127
	v_add_f32_e32 v124, 1.0, v124
	v_add_f32_e32 v125, 1.0, v125
	v_rcp_f32_e32 v124, v124
	v_rcp_f32_e32 v125, v125
	s_nop 0
	v_pk_mul_f32 v[120:121], v[120:121], v[124:125]
	v_mul_f32_e32 v124, 0xbfb8aa3b, v143
	v_exp_f32_e32 v124, v124
	v_mul_f32_e32 v125, 0xbfb8aa3b, v146
	v_exp_f32_e32 v125, v125
	v_add_f32_e32 v124, 1.0, v124
	v_rcp_f32_e32 v127, v124
	v_add_f32_e32 v125, 1.0, v125
	v_mul_f32_e32 v124, 0xbfb8aa3b, v130
	v_exp_f32_e32 v124, v124
	v_pk_mul_f32 v[116:117], v[116:117], v[126:127]
	v_rcp_f32_e32 v126, v125
	v_mul_f32_e32 v125, 0xbfb8aa3b, v131
	v_exp_f32_e32 v125, v125
	v_add_f32_e32 v124, 1.0, v124
	v_rcp_f32_e32 v124, v124
	v_add_f32_e32 v125, 1.0, v125
	v_rcp_f32_e32 v125, v125
	s_nop 0
	v_pk_mul_f32 v[122:123], v[122:123], v[124:125]
	v_mul_f32_e32 v124, 0xbfb8aa3b, v147
	v_exp_f32_e32 v124, v124
	s_nop 0
	v_add_f32_e32 v124, 1.0, v124
	v_rcp_f32_e32 v127, v124
	v_cndmask_b32_e64 v124, 0, 1, s[22:23]
	v_cmp_ne_u32_e64 s[6:7], 1, v124
	v_pk_mul_f32 v[118:119], v[118:119], v[126:127]
	s_cbranch_vccnz .LBB0_892
	s_ashr_i32 s9, s8, 31
	s_cmp_eq_u32 s48, 0
	s_cselect_b32 s13, 0, 0x100
	v_add_u32_e32 v124, s13, v148
	s_lshl_b64 s[22:23], s[8:9], 22
	v_ashrrev_i32_e32 v125, 31, v124
	s_add_u32 s22, s28, s22
	s_addc_u32 s23, s29, s23
	v_lshlrev_b64 v[124:125], 13, v[124:125]
	v_lshl_add_u64 v[124:125], s[22:23], 0, v[124:125]
	v_lshl_add_u64 v[124:125], v[140:141], 2, v[124:125]
	global_store_dwordx4 v[124:125], v[120:123], off offset:512
	global_store_dwordx4 v[124:125], v[116:119], off offset:528
	s_cbranch_execz .LBB0_893
	s_branch .LBB0_896

; __device__ __forceinline__ float sigm(float x) { return __builtin_amdgcn_rcpf(1.f + __expf(-x)); }
;     __device__ __forceinline__ void operator()(const f32x4 (&acc)[2][2][4][2], const Unit& u, int wr, int wc, int fr, int fq) const {
;     ...
;             for (int m = 0; m < 4; ++m) { const int row = row0 + ai * HALF + m * 16;
; #pragma unroll
;                 for (int bj = 0; bj < 2; ++bj) { const int col = col0 + bj * HALF;
;                     float gt[8]; unpack8(*(const u32x4*)(H + (size_t)row * NPAD + C_GATE + g * D + col), gt);
;                     float v[8];
; #pragma unroll
;                     for (int e = 0; e < 4; ++e) { v[e] = sigm(gt[e]) * acc[ai][bj][m][0][e]; v[4 + e] = sigm(gt[4 + e]) * acc[ai][bj][m][1][e]; }
;                     if (u.split) { float* cp = SCTX + ((size_t)u.slot * 512 + (row - u.pm * BM + (u.pm ? 256 : 0))) * D + col;
;                         *(f32x4*)cp = (f32x4){v[0], v[1], v[2], v[3]}; *(f32x4*)(cp + 4) = (f32x4){v[4], v[5], v[6], v[7]}; }
.LBB0_896:
	v_or_b32_e32 v116, 16, v142
	v_mov_b64_e32 v[118:119], s[60:61]
	v_mad_i64_i32 v[118:119], s[22:23], v116, s43, v[118:119]
	v_lshl_add_u64 v[118:119], s[20:21], 1, v[118:119]
	v_lshl_add_u64 v[120:121], v[140:141], 1, v[118:119]
	v_add_co_u32_e32 v118, vcc, 0x5000, v120
	s_nop 1
	v_addc_co_u32_e32 v119, vcc, 0, v121, vcc
	s_and_b64 vcc, exec, s[6:7]
	s_waitcnt vmcnt(5)
	v_mov_b64_e32 v[122:123], v[172:173]
	v_mov_b64_e32 v[124:125], v[174:175]
	v_lshlrev_b32_e32 v117, 16, v122
	v_mul_f32_e32 v117, 0xbfb8aa3b, v117
	v_exp_f32_e32 v117, v117
	v_and_b32_e32 v119, 0xffff0000, v122
	v_lshlrev_b32_e32 v122, 16, v124
	v_lshlrev_b32_e32 v126, 16, v123
	v_add_f32_e32 v117, 1.0, v117
	v_rcp_f32_e32 v118, v117
	v_mul_f32_e32 v117, 0xbfb8aa3b, v122
	v_exp_f32_e32 v117, v117
	v_and_b32_e32 v127, 0xffff0000, v123
	v_and_b32_e32 v123, 0xffff0000, v124
	v_lshlrev_b32_e32 v124, 16, v125
	v_add_f32_e32 v117, 1.0, v117
	v_rcp_f32_e32 v122, v117
	v_mul_f32_e32 v117, 0xbfb8aa3b, v119
	v_exp_f32_e32 v117, v117
	v_and_b32_e32 v125, 0xffff0000, v125
	v_add_f32_e32 v117, 1.0, v117
	v_rcp_f32_e32 v119, v117
	v_mul_f32_e32 v117, 0xbfb8aa3b, v123
	v_exp_f32_e32 v117, v117
	v_pk_mul_f32 v[112:113], v[112:113], v[118:119]
	v_add_f32_e32 v117, 1.0, v117
	v_rcp_f32_e32 v123, v117
	v_mul_f32_e32 v117, 0xbfb8aa3b, v126
	v_exp_f32_e32 v117, v117
	v_pk_mul_f32 v[108:109], v[108:109], v[122:123]
	v_add_f32_e32 v117, 1.0, v117
	v_rcp_f32_e32 v118, v117
	v_mul_f32_e32 v117, 0xbfb8aa3b, v124
	v_exp_f32_e32 v117, v117
	s_nop 0
	v_add_f32_e32 v117, 1.0, v117
	v_rcp_f32_e32 v122, v117
	v_mul_f32_e32 v117, 0xbfb8aa3b, v127
	v_exp_f32_e32 v117, v117
	s_nop 0
	v_add_f32_e32 v117, 1.0, v117
	v_rcp_f32_e32 v119, v117
	v_mul_f32_e32 v117, 0xbfb8aa3b, v125
	v_exp_f32_e32 v117, v117
	v_pk_mul_f32 v[114:115], v[114:115], v[118:119]
	v_add_f32_e32 v117, 1.0, v117
	v_rcp_f32_e32 v123, v117
	s_nop 0
	v_pk_mul_f32 v[110:111], v[110:111], v[122:123]
	s_cbranch_vccnz .LBB0_898
	s_ashr_i32 s9, s8, 31
	s_cmp_eq_u32 s48, 0
	s_cselect_b32 s13, 0, 0x100
	s_sub_i32 s13, s13, s11
	v_add_u32_e32 v118, s13, v116
	s_lshl_b64 s[22:23], s[8:9], 22
	v_ashrrev_i32_e32 v119, 31, v118
	s_add_u32 s22, s28, s22
	s_addc_u32 s23, s29, s23
	v_lshlrev_b64 v[118:119], 13, v[118:119]
	v_lshl_add_u64 v[118:119], s[22:23], 0, v[118:119]
	v_lshl_add_u64 v[118:119], v[140:141], 2, v[118:119]
	s_mov_b64 s[22:23], 0
	global_store_dwordx4 v[118:119], v[112:115], off
	global_store_dwordx4 v[118:119], v[108:111], off offset:16
	s_branch .LBB0_899

; __device__ __forceinline__ float sigm(float x) { return __builtin_amdgcn_rcpf(1.f + __expf(-x)); }
;     __device__ __forceinline__ void operator()(const f32x4 (&acc)[2][2][4][2], const Unit& u, int wr, int wc, int fr, int fq) const {
;     ...
;             for (int m = 0; m < 4; ++m) { const int row = row0 + ai * HALF + m * 16;
; #pragma unroll
;                 for (int bj = 0; bj < 2; ++bj) { const int col = col0 + bj * HALF;
;                     float gt[8]; unpack8(*(const u32x4*)(H + (size_t)row * NPAD + C_GATE + g * D + col), gt);
;                     float v[8];
; #pragma unroll
;                     for (int e = 0; e < 4; ++e) { v[e] = sigm(gt[e]) * acc[ai][bj][m][0][e]; v[4 + e] = sigm(gt[4 + e]) * acc[ai][bj][m][1][e]; }
;                     if (u.split) { float* cp = SCTX + ((size_t)u.slot * 512 + (row - u.pm * BM + (u.pm ? 256 : 0))) * D + col;
;                         *(f32x4*)cp = (f32x4){v[0], v[1], v[2], v[3]}; *(f32x4*)(cp + 4) = (f32x4){v[4], v[5], v[6], v[7]}; }
.LBB0_903:
	s_mov_b64 s[22:23], 0x5840
	v_lshl_add_u64 v[108:109], v[120:121], 0, s[22:23]
	s_and_b64 vcc, exec, s[6:7]
	s_waitcnt vmcnt(4)
	v_mov_b64_e32 v[108:109], v[176:177]
	v_mov_b64_e32 v[110:111], v[178:179]
	v_lshlrev_b32_e32 v114, 16, v109
	v_and_b32_e32 v115, 0xffff0000, v109
	v_lshlrev_b32_e32 v109, 16, v110
	v_mul_f32_e32 v109, 0xbfb8aa3b, v109
	v_exp_f32_e32 v109, v109
	v_lshlrev_b32_e32 v112, 16, v108
	v_and_b32_e32 v113, 0xffff0000, v108
	v_and_b32_e32 v117, 0xffff0000, v110
	v_add_f32_e32 v109, 1.0, v109
	v_mul_f32_e32 v108, 0xbfb8aa3b, v112
	v_rcp_f32_e32 v110, v109
	v_mul_f32_e32 v109, 0xbfb8aa3b, v113
	v_exp_f32_e32 v108, v108
	v_exp_f32_e32 v109, v109
	v_lshlrev_b32_e32 v120, 16, v111
	v_and_b32_e32 v121, 0xffff0000, v111
	v_add_f32_e32 v108, 1.0, v108
	v_add_f32_e32 v109, 1.0, v109
	v_rcp_f32_e32 v108, v108
	v_rcp_f32_e32 v109, v109
	s_nop 0
	v_pk_mul_f32 v[104:105], v[104:105], v[108:109]
	v_mul_f32_e32 v108, 0xbfb8aa3b, v117
	v_exp_f32_e32 v108, v108
	v_mul_f32_e32 v109, 0xbfb8aa3b, v120
	v_exp_f32_e32 v109, v109
	v_add_f32_e32 v108, 1.0, v108
	v_rcp_f32_e32 v111, v108
	v_add_f32_e32 v109, 1.0, v109
	v_mul_f32_e32 v108, 0xbfb8aa3b, v114
	v_exp_f32_e32 v108, v108
	v_pk_mul_f32 v[100:101], v[100:101], v[110:111]
	v_rcp_f32_e32 v110, v109
	v_mul_f32_e32 v109, 0xbfb8aa3b, v115
	v_exp_f32_e32 v109, v109
	v_add_f32_e32 v108, 1.0, v108
	v_rcp_f32_e32 v108, v108
	v_add_f32_e32 v109, 1.0, v109
	v_rcp_f32_e32 v109, v109
	s_nop 0
	v_pk_mul_f32 v[106:107], v[106:107], v[108:109]
	v_mul_f32_e32 v108, 0xbfb8aa3b, v121
	v_exp_f32_e32 v108, v108
	s_nop 0
	v_add_f32_e32 v108, 1.0, v108
	v_rcp_f32_e32 v111, v108
	s_nop 0
	v_pk_mul_f32 v[102:103], v[102:103], v[110:111]
	s_cbranch_vccnz .LBB0_905
	s_ashr_i32 s9, s8, 31
	s_cmp_eq_u32 s48, 0
	s_cselect_b32 s13, 0, 0x100
	s_sub_i32 s13, s13, s11
	v_add_u32_e32 v108, s13, v116
	s_lshl_b64 s[22:23], s[8:9], 22
	v_ashrrev_i32_e32 v109, 31, v108
	s_add_u32 s22, s28, s22
	s_addc_u32 s23, s29, s23
	v_lshlrev_b64 v[108:109], 13, v[108:109]
	v_lshl_add_u64 v[108:109], s[22:23], 0, v[108:109]
	v_lshl_add_u64 v[108:109], v[140:141], 2, v[108:109]
	global_store_dwordx4 v[108:109], v[104:107], off offset:512
	global_store_dwordx4 v[108:109], v[100:103], off offset:528
	s_cbranch_execz .LBB0_906
	s_branch .LBB0_909

; __device__ __forceinline__ float sigm(float x) { return __builtin_amdgcn_rcpf(1.f + __expf(-x)); }
;     __device__ __forceinline__ void operator()(const f32x4 (&acc)[2][2][4][2], const Unit& u, int wr, int wc, int fr, int fq) const {
;     ...
;             for (int m = 0; m < 4; ++m) { const int row = row0 + ai * HALF + m * 16;
; #pragma unroll
;                 for (int bj = 0; bj < 2; ++bj) { const int col = col0 + bj * HALF;
;                     float gt[8]; unpack8(*(const u32x4*)(H + (size_t)row * NPAD + C_GATE + g * D + col), gt);
;                     float v[8];
; #pragma unroll
;                     for (int e = 0; e < 4; ++e) { v[e] = sigm(gt[e]) * acc[ai][bj][m][0][e]; v[4 + e] = sigm(gt[4 + e]) * acc[ai][bj][m][1][e]; }
;                     if (u.split) { float* cp = SCTX + ((size_t)u.slot * 512 + (row - u.pm * BM + (u.pm ? 256 : 0))) * D + col;
;                         *(f32x4*)cp = (f32x4){v[0], v[1], v[2], v[3]}; *(f32x4*)(cp + 4) = (f32x4){v[4], v[5], v[6], v[7]}; }
.LBB0_909:
	v_or_b32_e32 v100, 32, v142
	v_mov_b64_e32 v[102:103], s[60:61]
	v_mad_i64_i32 v[102:103], s[22:23], v100, s43, v[102:103]
	v_lshl_add_u64 v[102:103], s[20:21], 1, v[102:103]
	v_lshl_add_u64 v[104:105], v[140:141], 1, v[102:103]
	v_add_co_u32_e32 v102, vcc, 0x5000, v104
	s_nop 1
	v_addc_co_u32_e32 v103, vcc, 0, v105, vcc
	s_and_b64 vcc, exec, s[6:7]
	s_waitcnt vmcnt(3)
	v_mov_b64_e32 v[106:107], v[180:181]
	v_mov_b64_e32 v[108:109], v[182:183]
	v_lshlrev_b32_e32 v101, 16, v106
	v_mul_f32_e32 v101, 0xbfb8aa3b, v101
	v_exp_f32_e32 v101, v101
	v_and_b32_e32 v103, 0xffff0000, v106
	v_lshlrev_b32_e32 v106, 16, v108
	v_lshlrev_b32_e32 v110, 16, v107
	v_add_f32_e32 v101, 1.0, v101
	v_rcp_f32_e32 v102, v101
	v_mul_f32_e32 v101, 0xbfb8aa3b, v106
	v_exp_f32_e32 v101, v101
	v_and_b32_e32 v111, 0xffff0000, v107
	v_and_b32_e32 v107, 0xffff0000, v108
	v_lshlrev_b32_e32 v108, 16, v109
	v_add_f32_e32 v101, 1.0, v101
	v_rcp_f32_e32 v106, v101
	v_mul_f32_e32 v101, 0xbfb8aa3b, v103
	v_exp_f32_e32 v101, v101
	v_and_b32_e32 v109, 0xffff0000, v109
	v_add_f32_e32 v101, 1.0, v101
	v_rcp_f32_e32 v103, v101
	v_mul_f32_e32 v101, 0xbfb8aa3b, v107
	v_exp_f32_e32 v101, v101
	v_pk_mul_f32 v[96:97], v[96:97], v[102:103]
	v_add_f32_e32 v101, 1.0, v101
	v_rcp_f32_e32 v107, v101
	v_mul_f32_e32 v101, 0xbfb8aa3b, v110
	v_exp_f32_e32 v101, v101
	v_pk_mul_f32 v[92:93], v[92:93], v[106:107]
	v_add_f32_e32 v101, 1.0, v101
	v_rcp_f32_e32 v102, v101
	v_mul_f32_e32 v101, 0xbfb8aa3b, v108
	v_exp_f32_e32 v101, v101
	s_nop 0
	v_add_f32_e32 v101, 1.0, v101
	v_rcp_f32_e32 v106, v101
	v_mul_f32_e32 v101, 0xbfb8aa3b, v111
	v_exp_f32_e32 v101, v101
	s_nop 0
	v_add_f32_e32 v101, 1.0, v101
	v_rcp_f32_e32 v103, v101
	v_mul_f32_e32 v101, 0xbfb8aa3b, v109
	v_exp_f32_e32 v101, v101
	v_pk_mul_f32 v[98:99], v[98:99], v[102:103]
	v_add_f32_e32 v101, 1.0, v101
	v_rcp_f32_e32 v107, v101
	s_nop 0
	v_pk_mul_f32 v[94:95], v[94:95], v[106:107]
	s_cbranch_vccnz .LBB0_911
	s_ashr_i32 s9, s8, 31
	s_cmp_eq_u32 s48, 0
	s_cselect_b32 s13, 0, 0x100
	s_sub_i32 s13, s13, s11
	v_add_u32_e32 v102, s13, v100
	s_lshl_b64 s[22:23], s[8:9], 22
	v_ashrrev_i32_e32 v103, 31, v102
	s_add_u32 s22, s28, s22
	s_addc_u32 s23, s29, s23
	v_lshlrev_b64 v[102:103], 13, v[102:103]
	v_lshl_add_u64 v[102:103], s[22:23], 0, v[102:103]
	v_lshl_add_u64 v[102:103], v[140:141], 2, v[102:103]
	s_mov_b64 s[22:23], 0
	global_store_dwordx4 v[102:103], v[96:99], off
	global_store_dwordx4 v[102:103], v[92:95], off offset:16
	s_branch .LBB0_912

; __device__ __forceinline__ float sigm(float x) { return __builtin_amdgcn_rcpf(1.f + __expf(-x)); }
;     __device__ __forceinline__ void operator()(const f32x4 (&acc)[2][2][4][2], const Unit& u, int wr, int wc, int fr, int fq) const {
;     ...
;             for (int m = 0; m < 4; ++m) { const int row = row0 + ai * HALF + m * 16;
; #pragma unroll
;                 for (int bj = 0; bj < 2; ++bj) { const int col = col0 + bj * HALF;
;                     float gt[8]; unpack8(*(const u32x4*)(H + (size_t)row * NPAD + C_GATE + g * D + col), gt);
;                     float v[8];
; #pragma unroll
;                     for (int e = 0; e < 4; ++e) { v[e] = sigm(gt[e]) * acc[ai][bj][m][0][e]; v[4 + e] = sigm(gt[4 + e]) * acc[ai][bj][m][1][e]; }
;                     if (u.split) { float* cp = SCTX + ((size_t)u.slot * 512 + (row - u.pm * BM + (u.pm ? 256 : 0))) * D + col;
;                         *(f32x4*)cp = (f32x4){v[0], v[1], v[2], v[3]}; *(f32x4*)(cp + 4) = (f32x4){v[4], v[5], v[6], v[7]}; }
.LBB0_916:
	s_mov_b64 s[22:23], 0x5840
	v_lshl_add_u64 v[92:93], v[104:105], 0, s[22:23]
	s_and_b64 vcc, exec, s[6:7]
	s_waitcnt vmcnt(2)
	v_mov_b64_e32 v[92:93], v[184:185]
	v_mov_b64_e32 v[94:95], v[186:187]
	v_lshlrev_b32_e32 v98, 16, v93
	v_and_b32_e32 v99, 0xffff0000, v93
	v_lshlrev_b32_e32 v93, 16, v94
	v_mul_f32_e32 v93, 0xbfb8aa3b, v93
	v_exp_f32_e32 v93, v93
	v_lshlrev_b32_e32 v96, 16, v92
	v_and_b32_e32 v97, 0xffff0000, v92
	v_and_b32_e32 v101, 0xffff0000, v94
	v_add_f32_e32 v93, 1.0, v93
	v_mul_f32_e32 v92, 0xbfb8aa3b, v96
	v_rcp_f32_e32 v94, v93
	v_mul_f32_e32 v93, 0xbfb8aa3b, v97
	v_exp_f32_e32 v92, v92
	v_exp_f32_e32 v93, v93
	v_lshlrev_b32_e32 v104, 16, v95
	v_and_b32_e32 v105, 0xffff0000, v95
	v_add_f32_e32 v92, 1.0, v92
	v_add_f32_e32 v93, 1.0, v93
	v_rcp_f32_e32 v92, v92
	v_rcp_f32_e32 v93, v93
	s_nop 0
	v_pk_mul_f32 v[88:89], v[88:89], v[92:93]
	v_mul_f32_e32 v92, 0xbfb8aa3b, v101
	v_exp_f32_e32 v92, v92
	v_mul_f32_e32 v93, 0xbfb8aa3b, v104
	v_exp_f32_e32 v93, v93
	v_add_f32_e32 v92, 1.0, v92
	v_rcp_f32_e32 v95, v92
	v_add_f32_e32 v93, 1.0, v93
	v_mul_f32_e32 v92, 0xbfb8aa3b, v98
	v_exp_f32_e32 v92, v92
	v_pk_mul_f32 v[84:85], v[84:85], v[94:95]
	v_rcp_f32_e32 v94, v93
	v_mul_f32_e32 v93, 0xbfb8aa3b, v99
	v_exp_f32_e32 v93, v93
	v_add_f32_e32 v92, 1.0, v92
	v_rcp_f32_e32 v92, v92
	v_add_f32_e32 v93, 1.0, v93
	v_rcp_f32_e32 v93, v93
	s_nop 0
	v_pk_mul_f32 v[90:91], v[90:91], v[92:93]
	v_mul_f32_e32 v92, 0xbfb8aa3b, v105
	v_exp_f32_e32 v92, v92
	s_nop 0
	v_add_f32_e32 v92, 1.0, v92
	v_rcp_f32_e32 v95, v92
	s_nop 0
	v_pk_mul_f32 v[86:87], v[86:87], v[94:95]
	s_cbranch_vccnz .LBB0_918
	s_ashr_i32 s9, s8, 31
	s_cmp_eq_u32 s48, 0
	s_cselect_b32 s13, 0, 0x100
	s_sub_i32 s13, s13, s11
	v_add_u32_e32 v92, s13, v100
	s_lshl_b64 s[22:23], s[8:9], 22
	v_ashrrev_i32_e32 v93, 31, v92
	s_add_u32 s22, s28, s22
	s_addc_u32 s23, s29, s23
	v_lshlrev_b64 v[92:93], 13, v[92:93]
	v_lshl_add_u64 v[92:93], s[22:23], 0, v[92:93]
	v_lshl_add_u64 v[92:93], v[140:141], 2, v[92:93]
	global_store_dwordx4 v[92:93], v[88:91], off offset:512
	global_store_dwordx4 v[92:93], v[84:87], off offset:528
	s_cbranch_execz .LBB0_919
	s_branch .LBB0_922

; __device__ __forceinline__ float sigm(float x) { return __builtin_amdgcn_rcpf(1.f + __expf(-x)); }
;     __device__ __forceinline__ void operator()(const f32x4 (&acc)[2][2][4][2], const Unit& u, int wr, int wc, int fr, int fq) const {
;     ...
;             for (int m = 0; m < 4; ++m) { const int row = row0 + ai * HALF + m * 16;
; #pragma unroll
;                 for (int bj = 0; bj < 2; ++bj) { const int col = col0 + bj * HALF;
;                     float gt[8]; unpack8(*(const u32x4*)(H + (size_t)row * NPAD + C_GATE + g * D + col), gt);
;                     float v[8];
; #pragma unroll
;                     for (int e = 0; e < 4; ++e) { v[e] = sigm(gt[e]) * acc[ai][bj][m][0][e]; v[4 + e] = sigm(gt[4 + e]) * acc[ai][bj][m][1][e]; }
;                     if (u.split) { float* cp = SCTX + ((size_t)u.slot * 512 + (row - u.pm * BM + (u.pm ? 256 : 0))) * D + col;
;                         *(f32x4*)cp = (f32x4){v[0], v[1], v[2], v[3]}; *(f32x4*)(cp + 4) = (f32x4){v[4], v[5], v[6], v[7]}; }
.LBB0_922:
	v_or_b32_e32 v84, 48, v142
	v_mov_b64_e32 v[86:87], s[60:61]
	v_mad_i64_i32 v[86:87], s[22:23], v84, s43, v[86:87]
	v_lshl_add_u64 v[86:87], s[20:21], 1, v[86:87]
	v_lshl_add_u64 v[88:89], v[140:141], 1, v[86:87]
	v_add_co_u32_e32 v86, vcc, 0x5000, v88
	s_nop 1
	v_addc_co_u32_e32 v87, vcc, 0, v89, vcc
	s_and_b64 vcc, exec, s[6:7]
	s_waitcnt vmcnt(1)
	v_mov_b64_e32 v[90:91], v[188:189]
	v_mov_b64_e32 v[92:93], v[190:191]
	v_lshlrev_b32_e32 v85, 16, v90
	v_mul_f32_e32 v85, 0xbfb8aa3b, v85
	v_exp_f32_e32 v85, v85
	v_and_b32_e32 v87, 0xffff0000, v90
	v_lshlrev_b32_e32 v90, 16, v92
	v_lshlrev_b32_e32 v94, 16, v91
	v_add_f32_e32 v85, 1.0, v85
	v_rcp_f32_e32 v86, v85
	v_mul_f32_e32 v85, 0xbfb8aa3b, v90
	v_exp_f32_e32 v85, v85
	v_and_b32_e32 v95, 0xffff0000, v91
	v_and_b32_e32 v91, 0xffff0000, v92
	v_lshlrev_b32_e32 v92, 16, v93
	v_add_f32_e32 v85, 1.0, v85
	v_rcp_f32_e32 v90, v85
	v_mul_f32_e32 v85, 0xbfb8aa3b, v87
	v_exp_f32_e32 v85, v85
	v_and_b32_e32 v93, 0xffff0000, v93
	v_add_f32_e32 v85, 1.0, v85
	v_rcp_f32_e32 v87, v85
	v_mul_f32_e32 v85, 0xbfb8aa3b, v91
	v_exp_f32_e32 v85, v85
	v_pk_mul_f32 v[80:81], v[80:81], v[86:87]
	v_add_f32_e32 v85, 1.0, v85
	v_rcp_f32_e32 v91, v85
	v_mul_f32_e32 v85, 0xbfb8aa3b, v94
	v_exp_f32_e32 v85, v85
	v_pk_mul_f32 v[76:77], v[76:77], v[90:91]
	v_add_f32_e32 v85, 1.0, v85
	v_rcp_f32_e32 v86, v85
	v_mul_f32_e32 v85, 0xbfb8aa3b, v92
	v_exp_f32_e32 v85, v85
	s_nop 0
	v_add_f32_e32 v85, 1.0, v85
	v_rcp_f32_e32 v90, v85
	v_mul_f32_e32 v85, 0xbfb8aa3b, v95
	v_exp_f32_e32 v85, v85
	s_nop 0
	v_add_f32_e32 v85, 1.0, v85
	v_rcp_f32_e32 v87, v85
	v_mul_f32_e32 v85, 0xbfb8aa3b, v93
	v_exp_f32_e32 v85, v85
	v_pk_mul_f32 v[82:83], v[82:83], v[86:87]
	v_add_f32_e32 v85, 1.0, v85
	v_rcp_f32_e32 v91, v85
	s_nop 0
	v_pk_mul_f32 v[78:79], v[78:79], v[90:91]
	s_cbranch_vccnz .LBB0_924
	s_ashr_i32 s9, s8, 31
	s_cmp_eq_u32 s48, 0
	s_cselect_b32 s13, 0, 0x100
	s_sub_i32 s13, s13, s11
	v_add_u32_e32 v86, s13, v84
	s_lshl_b64 s[22:23], s[8:9], 22
	v_ashrrev_i32_e32 v87, 31, v86
	s_add_u32 s22, s28, s22
	s_addc_u32 s23, s29, s23
	v_lshlrev_b64 v[86:87], 13, v[86:87]
	v_lshl_add_u64 v[86:87], s[22:23], 0, v[86:87]
	v_lshl_add_u64 v[86:87], v[140:141], 2, v[86:87]
	s_mov_b64 s[22:23], 0
	global_store_dwordx4 v[86:87], v[80:83], off
	global_store_dwordx4 v[86:87], v[76:79], off offset:16
	s_branch .LBB0_925

; __device__ __forceinline__ float sigm(float x) { return __builtin_amdgcn_rcpf(1.f + __expf(-x)); }
;     __device__ __forceinline__ void operator()(const f32x4 (&acc)[2][2][4][2], const Unit& u, int wr, int wc, int fr, int fq) const {
;     ...
;             for (int m = 0; m < 4; ++m) { const int row = row0 + ai * HALF + m * 16;
; #pragma unroll
;                 for (int bj = 0; bj < 2; ++bj) { const int col = col0 + bj * HALF;
;                     float gt[8]; unpack8(*(const u32x4*)(H + (size_t)row * NPAD + C_GATE + g * D + col), gt);
;                     float v[8];
; #pragma unroll
;                     for (int e = 0; e < 4; ++e) { v[e] = sigm(gt[e]) * acc[ai][bj][m][0][e]; v[4 + e] = sigm(gt[4 + e]) * acc[ai][bj][m][1][e]; }
;                     if (u.split) { float* cp = SCTX + ((size_t)u.slot * 512 + (row - u.pm * BM + (u.pm ? 256 : 0))) * D + col;
;                         *(f32x4*)cp = (f32x4){v[0], v[1], v[2], v[3]}; *(f32x4*)(cp + 4) = (f32x4){v[4], v[5], v[6], v[7]}; }
.LBB0_929:
	s_mov_b64 s[22:23], 0x5840
	v_lshl_add_u64 v[76:77], v[88:89], 0, s[22:23]
	s_and_b64 vcc, exec, s[6:7]
	s_waitcnt vmcnt(0)
	v_mov_b64_e32 v[76:77], v[192:193]
	v_mov_b64_e32 v[78:79], v[194:195]
	v_lshlrev_b32_e32 v82, 16, v77
	v_and_b32_e32 v83, 0xffff0000, v77
	v_lshlrev_b32_e32 v77, 16, v78
	v_mul_f32_e32 v77, 0xbfb8aa3b, v77
	v_exp_f32_e32 v77, v77
	v_lshlrev_b32_e32 v80, 16, v76
	v_and_b32_e32 v81, 0xffff0000, v76
	v_and_b32_e32 v85, 0xffff0000, v78
	v_add_f32_e32 v77, 1.0, v77
	v_mul_f32_e32 v76, 0xbfb8aa3b, v80
	v_rcp_f32_e32 v78, v77
	v_mul_f32_e32 v77, 0xbfb8aa3b, v81
	v_exp_f32_e32 v76, v76
	v_exp_f32_e32 v77, v77
	v_lshlrev_b32_e32 v88, 16, v79
	v_and_b32_e32 v89, 0xffff0000, v79
	v_add_f32_e32 v76, 1.0, v76
	v_add_f32_e32 v77, 1.0, v77
	v_rcp_f32_e32 v76, v76
	v_rcp_f32_e32 v77, v77
	s_nop 0
	v_pk_mul_f32 v[72:73], v[72:73], v[76:77]
	v_mul_f32_e32 v76, 0xbfb8aa3b, v85
	v_exp_f32_e32 v76, v76
	v_mul_f32_e32 v77, 0xbfb8aa3b, v88
	v_exp_f32_e32 v77, v77
	v_add_f32_e32 v76, 1.0, v76
	v_rcp_f32_e32 v79, v76
	v_add_f32_e32 v77, 1.0, v77
	v_mul_f32_e32 v76, 0xbfb8aa3b, v82
	v_exp_f32_e32 v76, v76
	v_pk_mul_f32 v[68:69], v[68:69], v[78:79]
	v_rcp_f32_e32 v78, v77
	v_mul_f32_e32 v77, 0xbfb8aa3b, v83
	v_exp_f32_e32 v77, v77
	v_add_f32_e32 v76, 1.0, v76
	v_rcp_f32_e32 v76, v76
	v_add_f32_e32 v77, 1.0, v77
	v_rcp_f32_e32 v77, v77
	s_nop 0
	v_pk_mul_f32 v[74:75], v[74:75], v[76:77]
	v_mul_f32_e32 v76, 0xbfb8aa3b, v89
	v_exp_f32_e32 v76, v76
	s_nop 0
	v_add_f32_e32 v76, 1.0, v76
	v_rcp_f32_e32 v79, v76
	s_nop 0
	v_pk_mul_f32 v[70:71], v[70:71], v[78:79]
	s_cbranch_vccnz .LBB0_931
	s_ashr_i32 s9, s8, 31
	s_cmp_eq_u32 s48, 0
	s_cselect_b32 s13, 0, 0x100
	s_sub_i32 s13, s13, s11
	v_add_u32_e32 v76, s13, v84
	s_lshl_b64 s[22:23], s[8:9], 22
	v_ashrrev_i32_e32 v77, 31, v76
	s_add_u32 s22, s28, s22
	s_addc_u32 s23, s29, s23
	v_lshlrev_b64 v[76:77], 13, v[76:77]
	v_lshl_add_u64 v[76:77], s[22:23], 0, v[76:77]
	v_lshl_add_u64 v[76:77], v[140:141], 2, v[76:77]
	global_store_dwordx4 v[76:77], v[72:75], off offset:512
	global_store_dwordx4 v[76:77], v[68:71], off offset:528
	s_cbranch_execz .LBB0_932
	s_branch .LBB0_935

; __device__ __forceinline__ float sigm(float x) { return __builtin_amdgcn_rcpf(1.f + __expf(-x)); }
;     __device__ __forceinline__ void operator()(const f32x4 (&acc)[2][2][4][2], const Unit& u, int wr, int wc, int fr, int fq) const {
;     ...
;             for (int m = 0; m < 4; ++m) { const int row = row0 + ai * HALF + m * 16;
; #pragma unroll
;                 for (int bj = 0; bj < 2; ++bj) { const int col = col0 + bj * HALF;
;                     float gt[8]; unpack8(*(const u32x4*)(H + (size_t)row * NPAD + C_GATE + g * D + col), gt);
;                     float v[8];
; #pragma unroll
;                     for (int e = 0; e < 4; ++e) { v[e] = sigm(gt[e]) * acc[ai][bj][m][0][e]; v[4 + e] = sigm(gt[4 + e]) * acc[ai][bj][m][1][e]; }
;                     if (u.split) { float* cp = SCTX + ((size_t)u.slot * 512 + (row - u.pm * BM + (u.pm ? 256 : 0))) * D + col;
;                         *(f32x4*)cp = (f32x4){v[0], v[1], v[2], v[3]}; *(f32x4*)(cp + 4) = (f32x4){v[4], v[5], v[6], v[7]}; }
.LBB0_935:
	s_mov_b64 s[22:23], 0x455840
	v_lshl_add_u64 v[216:217], v[214:215], 0, s[22:23]
	global_load_dwordx4 v[164:167], v[216:217], off
	global_load_dwordx4 v[168:171], v[216:217], off offset:256
	s_mov_b64 s[22:23], 0x4df840
	v_lshl_add_u64 v[216:217], v[214:215], 0, s[22:23]
	global_load_dwordx4 v[172:175], v[216:217], off
	global_load_dwordx4 v[176:179], v[216:217], off offset:256
	s_mov_b64 s[22:23], 0x569840
	v_lshl_add_u64 v[216:217], v[214:215], 0, s[22:23]
	global_load_dwordx4 v[180:183], v[216:217], off
	global_load_dwordx4 v[184:187], v[216:217], off offset:256
	s_mov_b64 s[22:23], 0x5f3840
	v_lshl_add_u64 v[216:217], v[214:215], 0, s[22:23]
	global_load_dwordx4 v[188:191], v[216:217], off
	global_load_dwordx4 v[192:195], v[216:217], off offset:256
	v_add_u32_e32 v68, 0x80, v142
	v_mov_b64_e32 v[70:71], s[60:61]
	v_mad_i64_i32 v[70:71], s[22:23], v68, s43, v[70:71]
	v_lshl_add_u64 v[70:71], s[20:21], 1, v[70:71]
	v_lshl_add_u64 v[72:73], v[140:141], 1, v[70:71]
	v_add_co_u32_e32 v70, vcc, 0x5000, v72
	s_nop 1
	v_addc_co_u32_e32 v71, vcc, 0, v73, vcc
	s_and_b64 vcc, exec, s[6:7]
	s_waitcnt vmcnt(7)
	v_mov_b64_e32 v[74:75], v[164:165]
	v_mov_b64_e32 v[76:77], v[166:167]
	v_lshlrev_b32_e32 v69, 16, v74
	v_mul_f32_e32 v69, 0xbfb8aa3b, v69
	v_exp_f32_e32 v69, v69
	v_and_b32_e32 v71, 0xffff0000, v74
	v_lshlrev_b32_e32 v74, 16, v76
	v_lshlrev_b32_e32 v78, 16, v75
	v_add_f32_e32 v69, 1.0, v69
	v_rcp_f32_e32 v70, v69
	v_mul_f32_e32 v69, 0xbfb8aa3b, v74
	v_exp_f32_e32 v69, v69
	v_and_b32_e32 v79, 0xffff0000, v75
	v_and_b32_e32 v75, 0xffff0000, v76
	v_lshlrev_b32_e32 v76, 16, v77
	v_add_f32_e32 v69, 1.0, v69
	v_rcp_f32_e32 v74, v69
	v_mul_f32_e32 v69, 0xbfb8aa3b, v71
	v_exp_f32_e32 v69, v69
	v_and_b32_e32 v77, 0xffff0000, v77
	v_add_f32_e32 v69, 1.0, v69
	v_rcp_f32_e32 v71, v69
	v_mul_f32_e32 v69, 0xbfb8aa3b, v75
	v_exp_f32_e32 v69, v69
	v_pk_mul_f32 v[64:65], v[64:65], v[70:71]
	v_add_f32_e32 v69, 1.0, v69
	v_rcp_f32_e32 v75, v69
	v_mul_f32_e32 v69, 0xbfb8aa3b, v78
	v_exp_f32_e32 v69, v69
	v_pk_mul_f32 v[60:61], v[60:61], v[74:75]
	v_add_f32_e32 v69, 1.0, v69
	v_rcp_f32_e32 v70, v69
	v_mul_f32_e32 v69, 0xbfb8aa3b, v76
	v_exp_f32_e32 v69, v69
	s_nop 0
	v_add_f32_e32 v69, 1.0, v69
	v_rcp_f32_e32 v74, v69
	v_mul_f32_e32 v69, 0xbfb8aa3b, v79
	v_exp_f32_e32 v69, v69
	s_nop 0
	v_add_f32_e32 v69, 1.0, v69
	v_rcp_f32_e32 v71, v69
	v_mul_f32_e32 v69, 0xbfb8aa3b, v77
	v_exp_f32_e32 v69, v69
	v_pk_mul_f32 v[66:67], v[66:67], v[70:71]
	v_add_f32_e32 v69, 1.0, v69
	v_rcp_f32_e32 v75, v69
	s_nop 0
	v_pk_mul_f32 v[62:63], v[62:63], v[74:75]
	s_cbranch_vccnz .LBB0_937
	s_ashr_i32 s9, s8, 31
	s_cmp_eq_u32 s48, 0
	s_cselect_b32 s13, 0, 0x100
	s_sub_i32 s13, s13, s11
	v_add_u32_e32 v70, s13, v68
	s_lshl_b64 s[22:23], s[8:9], 22
	v_ashrrev_i32_e32 v71, 31, v70
	s_add_u32 s22, s28, s22
	s_addc_u32 s23, s29, s23
	v_lshlrev_b64 v[70:71], 13, v[70:71]
	v_lshl_add_u64 v[70:71], s[22:23], 0, v[70:71]
	v_lshl_add_u64 v[70:71], v[140:141], 2, v[70:71]
	s_mov_b64 s[22:23], 0
	global_store_dwordx4 v[70:71], v[64:67], off
	global_store_dwordx4 v[70:71], v[60:63], off offset:16
	s_branch .LBB0_938

; __device__ __forceinline__ float sigm(float x) { return __builtin_amdgcn_rcpf(1.f + __expf(-x)); }
;     __device__ __forceinline__ void operator()(const f32x4 (&acc)[2][2][4][2], const Unit& u, int wr, int wc, int fr, int fq) const {
;     ...
;             for (int m = 0; m < 4; ++m) { const int row = row0 + ai * HALF + m * 16;
; #pragma unroll
;                 for (int bj = 0; bj < 2; ++bj) { const int col = col0 + bj * HALF;
;                     float gt[8]; unpack8(*(const u32x4*)(H + (size_t)row * NPAD + C_GATE + g * D + col), gt);
;                     float v[8];
; #pragma unroll
;                     for (int e = 0; e < 4; ++e) { v[e] = sigm(gt[e]) * acc[ai][bj][m][0][e]; v[4 + e] = sigm(gt[4 + e]) * acc[ai][bj][m][1][e]; }
;                     if (u.split) { float* cp = SCTX + ((size_t)u.slot * 512 + (row - u.pm * BM + (u.pm ? 256 : 0))) * D + col;
;                         *(f32x4*)cp = (f32x4){v[0], v[1], v[2], v[3]}; *(f32x4*)(cp + 4) = (f32x4){v[4], v[5], v[6], v[7]}; }
.LBB0_942:
	s_mov_b64 s[22:23], 0x5840
	v_lshl_add_u64 v[60:61], v[72:73], 0, s[22:23]
	s_and_b64 vcc, exec, s[6:7]
	s_waitcnt vmcnt(6)
	v_mov_b64_e32 v[60:61], v[168:169]
	v_mov_b64_e32 v[62:63], v[170:171]
	v_lshlrev_b32_e32 v66, 16, v61
	v_and_b32_e32 v67, 0xffff0000, v61
	v_lshlrev_b32_e32 v61, 16, v62
	v_mul_f32_e32 v61, 0xbfb8aa3b, v61
	v_exp_f32_e32 v61, v61
	v_lshlrev_b32_e32 v64, 16, v60
	v_and_b32_e32 v65, 0xffff0000, v60
	v_and_b32_e32 v69, 0xffff0000, v62
	v_add_f32_e32 v61, 1.0, v61
	v_mul_f32_e32 v60, 0xbfb8aa3b, v64
	v_rcp_f32_e32 v62, v61
	v_mul_f32_e32 v61, 0xbfb8aa3b, v65
	v_exp_f32_e32 v60, v60
	v_exp_f32_e32 v61, v61
	v_lshlrev_b32_e32 v72, 16, v63
	v_and_b32_e32 v73, 0xffff0000, v63
	v_add_f32_e32 v60, 1.0, v60
	v_add_f32_e32 v61, 1.0, v61
	v_rcp_f32_e32 v60, v60
	v_rcp_f32_e32 v61, v61
	s_nop 0
	v_pk_mul_f32 v[56:57], v[56:57], v[60:61]
	v_mul_f32_e32 v60, 0xbfb8aa3b, v69
	v_exp_f32_e32 v60, v60
	v_mul_f32_e32 v61, 0xbfb8aa3b, v72
	v_exp_f32_e32 v61, v61
	v_add_f32_e32 v60, 1.0, v60
	v_rcp_f32_e32 v63, v60
	v_add_f32_e32 v61, 1.0, v61
	v_mul_f32_e32 v60, 0xbfb8aa3b, v66
	v_exp_f32_e32 v60, v60
	v_pk_mul_f32 v[52:53], v[52:53], v[62:63]
	v_rcp_f32_e32 v62, v61
	v_mul_f32_e32 v61, 0xbfb8aa3b, v67
	v_exp_f32_e32 v61, v61
	v_add_f32_e32 v60, 1.0, v60
	v_rcp_f32_e32 v60, v60
	v_add_f32_e32 v61, 1.0, v61
	v_rcp_f32_e32 v61, v61
	s_nop 0
	v_pk_mul_f32 v[58:59], v[58:59], v[60:61]
	v_mul_f32_e32 v60, 0xbfb8aa3b, v73
	v_exp_f32_e32 v60, v60
	s_nop 0
	v_add_f32_e32 v60, 1.0, v60
	v_rcp_f32_e32 v63, v60
	s_nop 0
	v_pk_mul_f32 v[54:55], v[54:55], v[62:63]
	s_cbranch_vccnz .LBB0_944
	s_ashr_i32 s9, s8, 31
	s_cmp_eq_u32 s48, 0
	s_cselect_b32 s13, 0, 0x100
	s_sub_i32 s13, s13, s11
	v_add_u32_e32 v60, s13, v68
	s_lshl_b64 s[22:23], s[8:9], 22
	v_ashrrev_i32_e32 v61, 31, v60
	s_add_u32 s22, s28, s22
	s_addc_u32 s23, s29, s23
	v_lshlrev_b64 v[60:61], 13, v[60:61]
	v_lshl_add_u64 v[60:61], s[22:23], 0, v[60:61]
	v_lshl_add_u64 v[60:61], v[140:141], 2, v[60:61]
	global_store_dwordx4 v[60:61], v[56:59], off offset:512
	global_store_dwordx4 v[60:61], v[52:55], off offset:528
	s_cbranch_execz .LBB0_945
	s_branch .LBB0_948

; __device__ __forceinline__ float sigm(float x) { return __builtin_amdgcn_rcpf(1.f + __expf(-x)); }
;     __device__ __forceinline__ void operator()(const f32x4 (&acc)[2][2][4][2], const Unit& u, int wr, int wc, int fr, int fq) const {
;     ...
;             for (int m = 0; m < 4; ++m) { const int row = row0 + ai * HALF + m * 16;
; #pragma unroll
;                 for (int bj = 0; bj < 2; ++bj) { const int col = col0 + bj * HALF;
;                     float gt[8]; unpack8(*(const u32x4*)(H + (size_t)row * NPAD + C_GATE + g * D + col), gt);
;                     float v[8];
; #pragma unroll
;                     for (int e = 0; e < 4; ++e) { v[e] = sigm(gt[e]) * acc[ai][bj][m][0][e]; v[4 + e] = sigm(gt[4 + e]) * acc[ai][bj][m][1][e]; }
;                     if (u.split) { float* cp = SCTX + ((size_t)u.slot * 512 + (row - u.pm * BM + (u.pm ? 256 : 0))) * D + col;
;                         *(f32x4*)cp = (f32x4){v[0], v[1], v[2], v[3]}; *(f32x4*)(cp + 4) = (f32x4){v[4], v[5], v[6], v[7]}; }
.LBB0_948:
	v_add_u32_e32 v52, 0x90, v142
	v_mov_b64_e32 v[54:55], s[60:61]
	v_mad_i64_i32 v[54:55], s[22:23], v52, s43, v[54:55]
	v_lshl_add_u64 v[54:55], s[20:21], 1, v[54:55]
	v_lshl_add_u64 v[56:57], v[140:141], 1, v[54:55]
	v_add_co_u32_e32 v54, vcc, 0x5000, v56
	s_nop 1
	v_addc_co_u32_e32 v55, vcc, 0, v57, vcc
	s_and_b64 vcc, exec, s[6:7]
	s_waitcnt vmcnt(5)
	v_mov_b64_e32 v[58:59], v[172:173]
	v_mov_b64_e32 v[60:61], v[174:175]
	v_lshlrev_b32_e32 v53, 16, v58
	v_mul_f32_e32 v53, 0xbfb8aa3b, v53
	v_exp_f32_e32 v53, v53
	v_and_b32_e32 v55, 0xffff0000, v58
	v_lshlrev_b32_e32 v58, 16, v60
	v_lshlrev_b32_e32 v62, 16, v59
	v_add_f32_e32 v53, 1.0, v53
	v_rcp_f32_e32 v54, v53
	v_mul_f32_e32 v53, 0xbfb8aa3b, v58
	v_exp_f32_e32 v53, v53
	v_and_b32_e32 v63, 0xffff0000, v59
	v_and_b32_e32 v59, 0xffff0000, v60
	v_lshlrev_b32_e32 v60, 16, v61
	v_add_f32_e32 v53, 1.0, v53
	v_rcp_f32_e32 v58, v53
	v_mul_f32_e32 v53, 0xbfb8aa3b, v55
	v_exp_f32_e32 v53, v53
	v_and_b32_e32 v61, 0xffff0000, v61
	v_add_f32_e32 v53, 1.0, v53
	v_rcp_f32_e32 v55, v53
	v_mul_f32_e32 v53, 0xbfb8aa3b, v59
	v_exp_f32_e32 v53, v53
	v_pk_mul_f32 v[48:49], v[48:49], v[54:55]
	v_add_f32_e32 v53, 1.0, v53
	v_rcp_f32_e32 v59, v53
	v_mul_f32_e32 v53, 0xbfb8aa3b, v62
	v_exp_f32_e32 v53, v53
	v_pk_mul_f32 v[44:45], v[44:45], v[58:59]
	v_add_f32_e32 v53, 1.0, v53
	v_rcp_f32_e32 v54, v53
	v_mul_f32_e32 v53, 0xbfb8aa3b, v60
	v_exp_f32_e32 v53, v53
	s_nop 0
	v_add_f32_e32 v53, 1.0, v53
	v_rcp_f32_e32 v58, v53
	v_mul_f32_e32 v53, 0xbfb8aa3b, v63
	v_exp_f32_e32 v53, v53
	s_nop 0
	v_add_f32_e32 v53, 1.0, v53
	v_rcp_f32_e32 v55, v53
	v_mul_f32_e32 v53, 0xbfb8aa3b, v61
	v_exp_f32_e32 v53, v53
	v_pk_mul_f32 v[50:51], v[50:51], v[54:55]
	v_add_f32_e32 v53, 1.0, v53
	v_rcp_f32_e32 v59, v53
	s_nop 0
	v_pk_mul_f32 v[46:47], v[46:47], v[58:59]
	s_cbranch_vccnz .LBB0_950
	s_ashr_i32 s9, s8, 31
	s_cmp_eq_u32 s48, 0
	s_cselect_b32 s13, 0, 0x100
	s_sub_i32 s13, s13, s11
	v_add_u32_e32 v54, s13, v52
	s_lshl_b64 s[22:23], s[8:9], 22
	v_ashrrev_i32_e32 v55, 31, v54
	s_add_u32 s22, s28, s22
	s_addc_u32 s23, s29, s23
	v_lshlrev_b64 v[54:55], 13, v[54:55]
	v_lshl_add_u64 v[54:55], s[22:23], 0, v[54:55]
	v_lshl_add_u64 v[54:55], v[140:141], 2, v[54:55]
	s_mov_b64 s[22:23], 0
	global_store_dwordx4 v[54:55], v[48:51], off
	global_store_dwordx4 v[54:55], v[44:47], off offset:16
	s_branch .LBB0_951

; __device__ __forceinline__ float sigm(float x) { return __builtin_amdgcn_rcpf(1.f + __expf(-x)); }
;     __device__ __forceinline__ void operator()(const f32x4 (&acc)[2][2][4][2], const Unit& u, int wr, int wc, int fr, int fq) const {
;     ...
;             for (int m = 0; m < 4; ++m) { const int row = row0 + ai * HALF + m * 16;
; #pragma unroll
;                 for (int bj = 0; bj < 2; ++bj) { const int col = col0 + bj * HALF;
;                     float gt[8]; unpack8(*(const u32x4*)(H + (size_t)row * NPAD + C_GATE + g * D + col), gt);
;                     float v[8];
; #pragma unroll
;                     for (int e = 0; e < 4; ++e) { v[e] = sigm(gt[e]) * acc[ai][bj][m][0][e]; v[4 + e] = sigm(gt[4 + e]) * acc[ai][bj][m][1][e]; }
;                     if (u.split) { float* cp = SCTX + ((size_t)u.slot * 512 + (row - u.pm * BM + (u.pm ? 256 : 0))) * D + col;
;                         *(f32x4*)cp = (f32x4){v[0], v[1], v[2], v[3]}; *(f32x4*)(cp + 4) = (f32x4){v[4], v[5], v[6], v[7]}; }
.LBB0_955:
	s_mov_b64 s[22:23], 0x5840
	v_lshl_add_u64 v[44:45], v[56:57], 0, s[22:23]
	s_and_b64 vcc, exec, s[6:7]
	s_waitcnt vmcnt(4)
	v_mov_b64_e32 v[44:45], v[176:177]
	v_mov_b64_e32 v[46:47], v[178:179]
	v_lshlrev_b32_e32 v50, 16, v45
	v_and_b32_e32 v51, 0xffff0000, v45
	v_lshlrev_b32_e32 v45, 16, v46
	v_mul_f32_e32 v45, 0xbfb8aa3b, v45
	v_exp_f32_e32 v45, v45
	v_lshlrev_b32_e32 v48, 16, v44
	v_and_b32_e32 v49, 0xffff0000, v44
	v_and_b32_e32 v53, 0xffff0000, v46
	v_add_f32_e32 v45, 1.0, v45
	v_mul_f32_e32 v44, 0xbfb8aa3b, v48
	v_rcp_f32_e32 v46, v45
	v_mul_f32_e32 v45, 0xbfb8aa3b, v49
	v_exp_f32_e32 v44, v44
	v_exp_f32_e32 v45, v45
	v_lshlrev_b32_e32 v56, 16, v47
	v_and_b32_e32 v57, 0xffff0000, v47
	v_add_f32_e32 v44, 1.0, v44
	v_add_f32_e32 v45, 1.0, v45
	v_rcp_f32_e32 v44, v44
	v_rcp_f32_e32 v45, v45
	s_nop 0
	v_pk_mul_f32 v[40:41], v[40:41], v[44:45]
	v_mul_f32_e32 v44, 0xbfb8aa3b, v53
	v_exp_f32_e32 v44, v44
	v_mul_f32_e32 v45, 0xbfb8aa3b, v56
	v_exp_f32_e32 v45, v45
	v_add_f32_e32 v44, 1.0, v44
	v_rcp_f32_e32 v47, v44
	v_add_f32_e32 v45, 1.0, v45
	v_mul_f32_e32 v44, 0xbfb8aa3b, v50
	v_exp_f32_e32 v44, v44
	v_pk_mul_f32 v[36:37], v[36:37], v[46:47]
	v_rcp_f32_e32 v46, v45
	v_mul_f32_e32 v45, 0xbfb8aa3b, v51
	v_exp_f32_e32 v45, v45
	v_add_f32_e32 v44, 1.0, v44
	v_rcp_f32_e32 v44, v44
	v_add_f32_e32 v45, 1.0, v45
	v_rcp_f32_e32 v45, v45
	s_nop 0
	v_pk_mul_f32 v[42:43], v[42:43], v[44:45]
	v_mul_f32_e32 v44, 0xbfb8aa3b, v57
	v_exp_f32_e32 v44, v44
	s_nop 0
	v_add_f32_e32 v44, 1.0, v44
	v_rcp_f32_e32 v47, v44
	s_nop 0
	v_pk_mul_f32 v[38:39], v[38:39], v[46:47]
	s_cbranch_vccnz .LBB0_957
	s_ashr_i32 s9, s8, 31
	s_cmp_eq_u32 s48, 0
	s_cselect_b32 s13, 0, 0x100
	s_sub_i32 s13, s13, s11
	v_add_u32_e32 v44, s13, v52
	s_lshl_b64 s[22:23], s[8:9], 22
	v_ashrrev_i32_e32 v45, 31, v44
	s_add_u32 s22, s28, s22
	s_addc_u32 s23, s29, s23
	v_lshlrev_b64 v[44:45], 13, v[44:45]
	v_lshl_add_u64 v[44:45], s[22:23], 0, v[44:45]
	v_lshl_add_u64 v[44:45], v[140:141], 2, v[44:45]
	global_store_dwordx4 v[44:45], v[40:43], off offset:512
	global_store_dwordx4 v[44:45], v[36:39], off offset:528
	s_cbranch_execz .LBB0_958
	s_branch .LBB0_961

; __device__ __forceinline__ float sigm(float x) { return __builtin_amdgcn_rcpf(1.f + __expf(-x)); }
;     __device__ __forceinline__ void operator()(const f32x4 (&acc)[2][2][4][2], const Unit& u, int wr, int wc, int fr, int fq) const {
;     ...
;             for (int m = 0; m < 4; ++m) { const int row = row0 + ai * HALF + m * 16;
; #pragma unroll
;                 for (int bj = 0; bj < 2; ++bj) { const int col = col0 + bj * HALF;
;                     float gt[8]; unpack8(*(const u32x4*)(H + (size_t)row * NPAD + C_GATE + g * D + col), gt);
;                     float v[8];
; #pragma unroll
;                     for (int e = 0; e < 4; ++e) { v[e] = sigm(gt[e]) * acc[ai][bj][m][0][e]; v[4 + e] = sigm(gt[4 + e]) * acc[ai][bj][m][1][e]; }
;                     if (u.split) { float* cp = SCTX + ((size_t)u.slot * 512 + (row - u.pm * BM + (u.pm ? 256 : 0))) * D + col;
;                         *(f32x4*)cp = (f32x4){v[0], v[1], v[2], v[3]}; *(f32x4*)(cp + 4) = (f32x4){v[4], v[5], v[6], v[7]}; }
.LBB0_961:
	v_add_u32_e32 v36, 0xa0, v142
	v_mov_b64_e32 v[38:39], s[60:61]
	v_mad_i64_i32 v[38:39], s[22:23], v36, s43, v[38:39]
	v_lshl_add_u64 v[38:39], s[20:21], 1, v[38:39]
	v_lshl_add_u64 v[40:41], v[140:141], 1, v[38:39]
	v_add_co_u32_e32 v38, vcc, 0x5000, v40
	s_nop 1
	v_addc_co_u32_e32 v39, vcc, 0, v41, vcc
	s_and_b64 vcc, exec, s[6:7]
	s_waitcnt vmcnt(3)
	v_mov_b64_e32 v[42:43], v[180:181]
	v_mov_b64_e32 v[44:45], v[182:183]
	v_lshlrev_b32_e32 v37, 16, v42
	v_mul_f32_e32 v37, 0xbfb8aa3b, v37
	v_exp_f32_e32 v37, v37
	v_and_b32_e32 v39, 0xffff0000, v42
	v_lshlrev_b32_e32 v42, 16, v44
	v_lshlrev_b32_e32 v46, 16, v43
	v_add_f32_e32 v37, 1.0, v37
	v_rcp_f32_e32 v38, v37
	v_mul_f32_e32 v37, 0xbfb8aa3b, v42
	v_exp_f32_e32 v37, v37
	v_and_b32_e32 v47, 0xffff0000, v43
	v_and_b32_e32 v43, 0xffff0000, v44
	v_lshlrev_b32_e32 v44, 16, v45
	v_add_f32_e32 v37, 1.0, v37
	v_rcp_f32_e32 v42, v37
	v_mul_f32_e32 v37, 0xbfb8aa3b, v39
	v_exp_f32_e32 v37, v37
	v_and_b32_e32 v45, 0xffff0000, v45
	v_add_f32_e32 v37, 1.0, v37
	v_rcp_f32_e32 v39, v37
	v_mul_f32_e32 v37, 0xbfb8aa3b, v43
	v_exp_f32_e32 v37, v37
	v_pk_mul_f32 v[32:33], v[32:33], v[38:39]
	v_add_f32_e32 v37, 1.0, v37
	v_rcp_f32_e32 v43, v37
	v_mul_f32_e32 v37, 0xbfb8aa3b, v46
	v_exp_f32_e32 v37, v37
	v_pk_mul_f32 v[28:29], v[28:29], v[42:43]
	v_add_f32_e32 v37, 1.0, v37
	v_rcp_f32_e32 v38, v37
	v_mul_f32_e32 v37, 0xbfb8aa3b, v44
	v_exp_f32_e32 v37, v37
	s_nop 0
	v_add_f32_e32 v37, 1.0, v37
	v_rcp_f32_e32 v42, v37
	v_mul_f32_e32 v37, 0xbfb8aa3b, v47
	v_exp_f32_e32 v37, v37
	s_nop 0
	v_add_f32_e32 v37, 1.0, v37
	v_rcp_f32_e32 v39, v37
	v_mul_f32_e32 v37, 0xbfb8aa3b, v45
	v_exp_f32_e32 v37, v37
	v_pk_mul_f32 v[34:35], v[34:35], v[38:39]
	v_add_f32_e32 v37, 1.0, v37
	v_rcp_f32_e32 v43, v37
	s_nop 0
	v_pk_mul_f32 v[30:31], v[30:31], v[42:43]
	s_cbranch_vccnz .LBB0_963
	s_ashr_i32 s9, s8, 31
	s_cmp_eq_u32 s48, 0
	s_cselect_b32 s13, 0, 0x100
	s_sub_i32 s13, s13, s11
	v_add_u32_e32 v38, s13, v36
	s_lshl_b64 s[22:23], s[8:9], 22
	v_ashrrev_i32_e32 v39, 31, v38
	s_add_u32 s22, s28, s22
	s_addc_u32 s23, s29, s23
	v_lshlrev_b64 v[38:39], 13, v[38:39]
	v_lshl_add_u64 v[38:39], s[22:23], 0, v[38:39]
	v_lshl_add_u64 v[38:39], v[140:141], 2, v[38:39]
	s_mov_b64 s[22:23], 0
	global_store_dwordx4 v[38:39], v[32:35], off
	global_store_dwordx4 v[38:39], v[28:31], off offset:16
	s_branch .LBB0_964

; __device__ __forceinline__ float sigm(float x) { return __builtin_amdgcn_rcpf(1.f + __expf(-x)); }
;     __device__ __forceinline__ void operator()(const f32x4 (&acc)[2][2][4][2], const Unit& u, int wr, int wc, int fr, int fq) const {
;     ...
;             for (int m = 0; m < 4; ++m) { const int row = row0 + ai * HALF + m * 16;
; #pragma unroll
;                 for (int bj = 0; bj < 2; ++bj) { const int col = col0 + bj * HALF;
;                     float gt[8]; unpack8(*(const u32x4*)(H + (size_t)row * NPAD + C_GATE + g * D + col), gt);
;                     float v[8];
; #pragma unroll
;                     for (int e = 0; e < 4; ++e) { v[e] = sigm(gt[e]) * acc[ai][bj][m][0][e]; v[4 + e] = sigm(gt[4 + e]) * acc[ai][bj][m][1][e]; }
;                     if (u.split) { float* cp = SCTX + ((size_t)u.slot * 512 + (row - u.pm * BM + (u.pm ? 256 : 0))) * D + col;
;                         *(f32x4*)cp = (f32x4){v[0], v[1], v[2], v[3]}; *(f32x4*)(cp + 4) = (f32x4){v[4], v[5], v[6], v[7]}; }
.LBB0_968:
	s_mov_b64 s[22:23], 0x5840
	v_lshl_add_u64 v[28:29], v[40:41], 0, s[22:23]
	s_and_b64 vcc, exec, s[6:7]
	s_waitcnt vmcnt(2)
	v_mov_b64_e32 v[28:29], v[184:185]
	v_mov_b64_e32 v[30:31], v[186:187]
	v_lshlrev_b32_e32 v34, 16, v29
	v_and_b32_e32 v35, 0xffff0000, v29
	v_lshlrev_b32_e32 v29, 16, v30
	v_mul_f32_e32 v29, 0xbfb8aa3b, v29
	v_exp_f32_e32 v29, v29
	v_lshlrev_b32_e32 v32, 16, v28
	v_and_b32_e32 v33, 0xffff0000, v28
	v_and_b32_e32 v37, 0xffff0000, v30
	v_add_f32_e32 v29, 1.0, v29
	v_mul_f32_e32 v28, 0xbfb8aa3b, v32
	v_rcp_f32_e32 v30, v29
	v_mul_f32_e32 v29, 0xbfb8aa3b, v33
	v_exp_f32_e32 v28, v28
	v_exp_f32_e32 v29, v29
	v_lshlrev_b32_e32 v40, 16, v31
	v_and_b32_e32 v41, 0xffff0000, v31
	v_add_f32_e32 v28, 1.0, v28
	v_add_f32_e32 v29, 1.0, v29
	v_rcp_f32_e32 v28, v28
	v_rcp_f32_e32 v29, v29
	s_nop 0
	v_pk_mul_f32 v[24:25], v[24:25], v[28:29]
	v_mul_f32_e32 v28, 0xbfb8aa3b, v37
	v_exp_f32_e32 v28, v28
	v_mul_f32_e32 v29, 0xbfb8aa3b, v40
	v_exp_f32_e32 v29, v29
	v_add_f32_e32 v28, 1.0, v28
	v_rcp_f32_e32 v31, v28
	v_add_f32_e32 v29, 1.0, v29
	v_mul_f32_e32 v28, 0xbfb8aa3b, v34
	v_exp_f32_e32 v28, v28
	v_pk_mul_f32 v[20:21], v[20:21], v[30:31]
	v_rcp_f32_e32 v30, v29
	v_mul_f32_e32 v29, 0xbfb8aa3b, v35
	v_exp_f32_e32 v29, v29
	v_add_f32_e32 v28, 1.0, v28
	v_rcp_f32_e32 v28, v28
	v_add_f32_e32 v29, 1.0, v29
	v_rcp_f32_e32 v29, v29
	s_nop 0
	v_pk_mul_f32 v[26:27], v[26:27], v[28:29]
	v_mul_f32_e32 v28, 0xbfb8aa3b, v41
	v_exp_f32_e32 v28, v28
	s_nop 0
	v_add_f32_e32 v28, 1.0, v28
	v_rcp_f32_e32 v31, v28
	s_nop 0
	v_pk_mul_f32 v[22:23], v[22:23], v[30:31]
	s_cbranch_vccnz .LBB0_970
	s_ashr_i32 s9, s8, 31
	s_cmp_eq_u32 s48, 0
	s_cselect_b32 s13, 0, 0x100
	s_sub_i32 s13, s13, s11
	v_add_u32_e32 v28, s13, v36
	s_lshl_b64 s[22:23], s[8:9], 22
	v_ashrrev_i32_e32 v29, 31, v28
	s_add_u32 s22, s28, s22
	s_addc_u32 s23, s29, s23
	v_lshlrev_b64 v[28:29], 13, v[28:29]
	v_lshl_add_u64 v[28:29], s[22:23], 0, v[28:29]
	v_lshl_add_u64 v[28:29], v[140:141], 2, v[28:29]
	global_store_dwordx4 v[28:29], v[24:27], off offset:512
	global_store_dwordx4 v[28:29], v[20:23], off offset:528
	s_cbranch_execz .LBB0_971
	s_branch .LBB0_974

; __device__ __forceinline__ float sigm(float x) { return __builtin_amdgcn_rcpf(1.f + __expf(-x)); }
;     __device__ __forceinline__ void operator()(const f32x4 (&acc)[2][2][4][2], const Unit& u, int wr, int wc, int fr, int fq) const {
;     ...
;             for (int m = 0; m < 4; ++m) { const int row = row0 + ai * HALF + m * 16;
; #pragma unroll
;                 for (int bj = 0; bj < 2; ++bj) { const int col = col0 + bj * HALF;
;                     float gt[8]; unpack8(*(const u32x4*)(H + (size_t)row * NPAD + C_GATE + g * D + col), gt);
;                     float v[8];
; #pragma unroll
;                     for (int e = 0; e < 4; ++e) { v[e] = sigm(gt[e]) * acc[ai][bj][m][0][e]; v[4 + e] = sigm(gt[4 + e]) * acc[ai][bj][m][1][e]; }
;                     if (u.split) { float* cp = SCTX + ((size_t)u.slot * 512 + (row - u.pm * BM + (u.pm ? 256 : 0))) * D + col;
;                         *(f32x4*)cp = (f32x4){v[0], v[1], v[2], v[3]}; *(f32x4*)(cp + 4) = (f32x4){v[4], v[5], v[6], v[7]}; }
.LBB0_974:
	v_add_u32_e32 v20, 0xb0, v142
	v_mov_b64_e32 v[22:23], s[60:61]
	v_mad_i64_i32 v[22:23], s[22:23], v20, s43, v[22:23]
	v_lshl_add_u64 v[22:23], s[20:21], 1, v[22:23]
	v_lshl_add_u64 v[24:25], v[140:141], 1, v[22:23]
	v_add_co_u32_e32 v22, vcc, 0x5000, v24
	s_nop 1
	v_addc_co_u32_e32 v23, vcc, 0, v25, vcc
	s_and_b64 vcc, exec, s[6:7]
	s_waitcnt vmcnt(1)
	v_mov_b64_e32 v[26:27], v[188:189]
	v_mov_b64_e32 v[28:29], v[190:191]
	v_lshlrev_b32_e32 v21, 16, v26
	v_mul_f32_e32 v21, 0xbfb8aa3b, v21
	v_exp_f32_e32 v21, v21
	v_and_b32_e32 v23, 0xffff0000, v26
	v_lshlrev_b32_e32 v26, 16, v28
	v_lshlrev_b32_e32 v30, 16, v27
	v_add_f32_e32 v21, 1.0, v21
	v_rcp_f32_e32 v22, v21
	v_mul_f32_e32 v21, 0xbfb8aa3b, v26
	v_exp_f32_e32 v21, v21
	v_and_b32_e32 v31, 0xffff0000, v27
	v_and_b32_e32 v27, 0xffff0000, v28
	v_lshlrev_b32_e32 v28, 16, v29
	v_add_f32_e32 v21, 1.0, v21
	v_rcp_f32_e32 v26, v21
	v_mul_f32_e32 v21, 0xbfb8aa3b, v23
	v_exp_f32_e32 v21, v21
	v_and_b32_e32 v29, 0xffff0000, v29
	v_add_f32_e32 v21, 1.0, v21
	v_rcp_f32_e32 v23, v21
	v_mul_f32_e32 v21, 0xbfb8aa3b, v27
	v_exp_f32_e32 v21, v21
	v_pk_mul_f32 v[16:17], v[16:17], v[22:23]
	v_add_f32_e32 v21, 1.0, v21
	v_rcp_f32_e32 v27, v21
	v_mul_f32_e32 v21, 0xbfb8aa3b, v30
	v_exp_f32_e32 v21, v21
	v_pk_mul_f32 v[12:13], v[12:13], v[26:27]
	v_add_f32_e32 v21, 1.0, v21
	v_rcp_f32_e32 v22, v21
	v_mul_f32_e32 v21, 0xbfb8aa3b, v28
	v_exp_f32_e32 v21, v21
	s_nop 0
	v_add_f32_e32 v21, 1.0, v21
	v_rcp_f32_e32 v26, v21
	v_mul_f32_e32 v21, 0xbfb8aa3b, v31
	v_exp_f32_e32 v21, v21
	s_nop 0
	v_add_f32_e32 v21, 1.0, v21
	v_rcp_f32_e32 v23, v21
	v_mul_f32_e32 v21, 0xbfb8aa3b, v29
	v_exp_f32_e32 v21, v21
	v_pk_mul_f32 v[18:19], v[18:19], v[22:23]
	v_add_f32_e32 v21, 1.0, v21
	v_rcp_f32_e32 v27, v21
	s_nop 0
	v_pk_mul_f32 v[14:15], v[14:15], v[26:27]
	s_cbranch_vccnz .LBB0_976
	s_ashr_i32 s9, s8, 31
	s_cmp_eq_u32 s48, 0
	s_cselect_b32 s13, 0, 0x100
	s_sub_i32 s13, s13, s11
	v_add_u32_e32 v22, s13, v20
	s_lshl_b64 s[20:21], s[8:9], 22
	v_ashrrev_i32_e32 v23, 31, v22
	s_add_u32 s20, s28, s20
	s_addc_u32 s21, s29, s21
	v_lshlrev_b64 v[22:23], 13, v[22:23]
	v_lshl_add_u64 v[22:23], s[20:21], 0, v[22:23]
	v_lshl_add_u64 v[22:23], v[140:141], 2, v[22:23]
	s_mov_b64 s[20:21], 0
	global_store_dwordx4 v[22:23], v[16:19], off
	global_store_dwordx4 v[22:23], v[12:15], off offset:16
	s_branch .LBB0_977

; __device__ __forceinline__ float sigm(float x) { return __builtin_amdgcn_rcpf(1.f + __expf(-x)); }
;     __device__ __forceinline__ void operator()(const f32x4 (&acc)[2][2][4][2], const Unit& u, int wr, int wc, int fr, int fq) const {
;     ...
;             for (int m = 0; m < 4; ++m) { const int row = row0 + ai * HALF + m * 16;
; #pragma unroll
;                 for (int bj = 0; bj < 2; ++bj) { const int col = col0 + bj * HALF;
;                     float gt[8]; unpack8(*(const u32x4*)(H + (size_t)row * NPAD + C_GATE + g * D + col), gt);
;                     float v[8];
; #pragma unroll
;                     for (int e = 0; e < 4; ++e) { v[e] = sigm(gt[e]) * acc[ai][bj][m][0][e]; v[4 + e] = sigm(gt[4 + e]) * acc[ai][bj][m][1][e]; }
;                     if (u.split) { float* cp = SCTX + ((size_t)u.slot * 512 + (row - u.pm * BM + (u.pm ? 256 : 0))) * D + col;
;                         *(f32x4*)cp = (f32x4){v[0], v[1], v[2], v[3]}; *(f32x4*)(cp + 4) = (f32x4){v[4], v[5], v[6], v[7]}; }
.LBB0_981:
	s_mov_b64 s[20:21], 0x5840
	v_lshl_add_u64 v[12:13], v[24:25], 0, s[20:21]
	s_and_b64 vcc, exec, s[6:7]
	s_waitcnt vmcnt(0)
	v_mov_b64_e32 v[12:13], v[192:193]
	v_mov_b64_e32 v[14:15], v[194:195]
	v_lshlrev_b32_e32 v18, 16, v13
	v_and_b32_e32 v19, 0xffff0000, v13
	v_lshlrev_b32_e32 v13, 16, v14
	v_mul_f32_e32 v13, 0xbfb8aa3b, v13
	v_exp_f32_e32 v13, v13
	v_lshlrev_b32_e32 v16, 16, v12
	v_and_b32_e32 v17, 0xffff0000, v12
	v_and_b32_e32 v21, 0xffff0000, v14
	v_add_f32_e32 v13, 1.0, v13
	v_mul_f32_e32 v12, 0xbfb8aa3b, v16
	v_rcp_f32_e32 v14, v13
	v_mul_f32_e32 v13, 0xbfb8aa3b, v17
	v_exp_f32_e32 v12, v12
	v_exp_f32_e32 v13, v13
	v_lshlrev_b32_e32 v24, 16, v15
	v_and_b32_e32 v25, 0xffff0000, v15
	v_add_f32_e32 v12, 1.0, v12
	v_add_f32_e32 v13, 1.0, v13
	v_rcp_f32_e32 v12, v12
	v_rcp_f32_e32 v13, v13
	s_nop 0
	v_pk_mul_f32 v[8:9], v[8:9], v[12:13]
	v_mul_f32_e32 v12, 0xbfb8aa3b, v21
	v_exp_f32_e32 v12, v12
	v_mul_f32_e32 v13, 0xbfb8aa3b, v24
	v_exp_f32_e32 v13, v13
	v_add_f32_e32 v12, 1.0, v12
	v_rcp_f32_e32 v15, v12
	v_add_f32_e32 v13, 1.0, v13
	v_mul_f32_e32 v12, 0xbfb8aa3b, v18
	v_exp_f32_e32 v12, v12
	v_pk_mul_f32 v[4:5], v[4:5], v[14:15]
	v_rcp_f32_e32 v14, v13
	v_mul_f32_e32 v13, 0xbfb8aa3b, v19
	v_exp_f32_e32 v13, v13
	v_add_f32_e32 v12, 1.0, v12
	v_rcp_f32_e32 v12, v12
	v_add_f32_e32 v13, 1.0, v13
	v_rcp_f32_e32 v13, v13
	s_nop 0
	v_pk_mul_f32 v[10:11], v[10:11], v[12:13]
	v_mul_f32_e32 v12, 0xbfb8aa3b, v25
	v_exp_f32_e32 v12, v12
	s_nop 0
	v_add_f32_e32 v12, 1.0, v12
	v_rcp_f32_e32 v15, v12
	s_nop 0
	v_pk_mul_f32 v[6:7], v[6:7], v[14:15]
	s_cbranch_vccnz .LBB0_983
	s_ashr_i32 s9, s8, 31
	s_cmp_eq_u32 s48, 0
	s_cselect_b32 s6, 0, 0x100
	s_sub_i32 s6, s6, s11
	v_add_u32_e32 v12, s6, v20
	s_lshl_b64 s[6:7], s[8:9], 22
	v_ashrrev_i32_e32 v13, 31, v12
	s_add_u32 s6, s28, s6
	s_addc_u32 s7, s29, s7
	v_lshlrev_b64 v[12:13], 13, v[12:13]
	v_lshl_add_u64 v[12:13], s[6:7], 0, v[12:13]
	v_lshl_add_u64 v[12:13], v[140:141], 2, v[12:13]
	global_store_dwordx4 v[12:13], v[8:11], off offset:512
	global_store_dwordx4 v[12:13], v[4:7], off offset:528
	s_cbranch_execnz .LBB0_860
	s_branch .LBB0_984
